# speedup vs baseline: 1.0019x; 1.0011x over previous
.Lp8b_eb_ok:
	s_cmp_ge_i32 s0, s9
	s_cbranch_scc1 .LBB0_898
	ds_read_b32 v0, v169
	v_mov_b32_e32 v115, v144
	v_readlane_b32 s34, v208, 46
	v_readlane_b32 s35, v208, 47
	v_readlane_b32 s44, v209, 0
	s_waitcnt lgkmcnt(0)
	v_readfirstlane_b32 s1, v0
	s_cmp_gt_i32 s1, s0
	s_cselect_b32 s1, 0, 32
	s_lshl_b32 s14, s1, 2
	s_or_b32 s14, s14, 0x13040
	v_mov_b32_e32 v0, s14
	ds_read_b32 v0, v0
	s_or_b32 s13, s1, 16
	v_readlane_b32 s48, v209, 4
	v_readlane_b32 s49, v209, 5
	v_mov_b32_e32 v32, v144
	s_waitcnt lgkmcnt(0)
	v_readfirstlane_b32 s14, v0
	s_cmp_gt_i32 s14, s0
	s_cselect_b32 s1, s1, s13
	s_lshl_b32 s14, s1, 2
	s_or_b32 s14, s14, 0x13020
	v_mov_b32_e32 v0, s14
	ds_read_b32 v0, v0
	s_or_b32 s13, s1, 8
	v_readlane_b32 s45, v209, 1
	v_readlane_b32 s46, v209, 2
	v_readlane_b32 s47, v209, 3
	s_waitcnt lgkmcnt(0)
	v_readfirstlane_b32 s14, v0
	s_cmp_gt_i32 s14, s0
	s_cselect_b32 s1, s1, s13
	s_lshl_b32 s14, s1, 2
	s_or_b32 s14, s14, 0x13010
	v_mov_b32_e32 v0, s14
	ds_read_b32 v0, v0
	s_or_b32 s13, s1, 4
	v_readlane_b32 s50, v209, 6
	v_readlane_b32 s51, v209, 7
	s_waitcnt lgkmcnt(0)
	v_readfirstlane_b32 s14, v0
	s_cmp_gt_i32 s14, s0
	s_cselect_b32 s1, s1, s13
	s_lshl_b32 s14, s1, 2
	s_add_i32 s14, s14, 0x13008
	v_mov_b32_e32 v0, s14
	ds_read_b32 v0, v0
	s_add_i32 s13, s1, 2
	s_waitcnt lgkmcnt(0)
	v_readfirstlane_b32 s14, v0
	s_cmp_gt_i32 s14, s0
	s_cselect_b32 s1, s1, s13
	s_lshl_b32 s14, s1, 2
	s_add_i32 s14, s14, 0x13004
	v_mov_b32_e32 v0, s14
	ds_read_b32 v0, v0
	s_add_i32 s13, s1, 1
	s_waitcnt lgkmcnt(0)
	v_readfirstlane_b32 s14, v0
	s_cmp_gt_i32 s14, s0
	s_cselect_b32 s16, s1, s13
	s_lshl_b32 s1, s16, 2
	s_add_i32 s1, s1, 0x13000
	v_mov_b32_e32 v0, s1
	ds_read_b32 v2, v0
	s_lshl_b64 s[14:15], s[16:17], 16
	s_add_u32 s14, s56, s14
	s_addc_u32 s15, s57, s15
	s_waitcnt lgkmcnt(0)
	v_sub_u32_e32 v2, s0, v2
	v_lshlrev_b32_e32 v2, 7, v2
	v_ashrrev_i32_e32 v3, 31, v2
	v_readfirstlane_b32 s13, v115
	v_and_b32_e32 v6, 31, v115
	v_lshlrev_b64 v[4:5], 2, v[2:3]
	ds_read_b32 v7, v0 offset:260
	v_lshl_add_u64 v[4:5], s[14:15], 0, v[4:5]
	v_and_or_b32 v0, s13, 64, v6
	v_lshlrev_b32_e32 v6, 2, v0
	v_readfirstlane_b32 s14, v4
	v_readfirstlane_b32 s15, v5
	v_or_b32_e32 v4, v0, v2
	s_waitcnt lgkmcnt(0)
	v_cmp_lt_i32_e32 vcc, v4, v7
	s_ashr_i32 s1, s0, 31
	s_lshl_b64 s[0:1], s[0:1], 16
	global_load_dword v3, v6, s[14:15]
	s_waitcnt vmcnt(0)
	v_cndmask_b32_e32 v120, -1, v3, vcc
	v_max_i32_e32 v0, 0, v120
	v_lshl_add_u64 v[2:3], v[0:1], 2, s[34:35]
	global_load_dword v116, v[2:3], off
	global_load_dword v0, v6, s[14:15] offset:128
	v_or_b32_e32 v2, 32, v4
	v_cmp_lt_i32_e32 vcc, v2, v7
	s_add_i32 s14, s16, s8
	s_ashr_i32 s15, s14, 31
	s_waitcnt vmcnt(0)
	v_cndmask_b32_e32 v118, -1, v0, vcc
	v_max_i32_e32 v0, 0, v118
	v_lshl_add_u64 v[2:3], v[0:1], 2, s[34:35]
	global_load_dword v114, v[2:3], off
	s_lshl_b64 s[34:35], s[14:15], 20
	s_and_b32 s14, s11, 0x380
	v_ashrrev_i32_e32 v2, 3, v115
	s_add_u32 s0, s78, s0
	v_ashrrev_i32_e32 v3, 31, v2
	s_addc_u32 s1, s79, s1
	v_lshlrev_b64 v[2:3], 9, v[2:3]
	v_lshl_add_u64 v[2:3], s[0:1], 0, v[2:3]
	s_add_u32 s0, s48, s34
	s_addc_u32 s1, s49, s35
	s_lshl_b32 s15, s14, 2
	s_add_u32 s0, s0, s15
	v_lshlrev_b32_e32 v0, 4, v115
	s_addc_u32 s1, s1, 0
	v_ashrrev_i32_e32 v30, 5, v32
	v_and_b32_e32 v0, 0x1f0, v0
	v_ashrrev_i32_e32 v31, 31, v30
	v_lshl_add_u64 v[4:5], s[0:1], 0, v[0:1]
	v_lshlrev_b64 v[6:7], 12, v[30:31]
	v_lshl_add_u64 v[124:125], v[4:5], 0, v[6:7]
	v_add_co_u32_e32 v126, vcc, s72, v124
	global_load_dwordx4 v[18:21], v[124:125], off
	s_nop 0
	v_addc_co_u32_e32 v127, vcc, 0, v125, vcc
	v_add_co_u32_e32 v128, vcc, s33, v124
	s_mov_b32 s1, 0x28000
	s_nop 0
	v_addc_co_u32_e32 v129, vcc, 0, v125, vcc
	v_add_co_u32_e32 v130, vcc, s36, v124
	v_lshlrev_b32_e32 v0, 4, v32
	s_nop 0
	v_addc_co_u32_e32 v131, vcc, 0, v125, vcc
	v_add_co_u32_e32 v132, vcc, s87, v124
	v_and_b32_e32 v0, 0x70, v0
	s_nop 0
	v_addc_co_u32_e32 v133, vcc, 0, v125, vcc
	v_add_co_u32_e32 v134, vcc, s1, v124
	s_mov_b32 s1, 0x30000
	s_nop 0
	v_addc_co_u32_e32 v135, vcc, 0, v125, vcc
	v_lshl_add_u64 v[122:123], v[2:3], 0, v[0:1]
	global_load_dwordx4 v[2:5], v[126:127], off
	v_add_co_u32_e32 v136, vcc, s1, v124
	global_load_dwordx4 v[6:9], v[128:129], off
	global_load_dwordx4 v[10:13], v[130:131], off
	v_addc_co_u32_e32 v137, vcc, 0, v125, vcc
	s_mov_b32 s1, 0x38000
	global_load_dwordx4 v[14:17], v[132:133], off
	global_load_dwordx4 v[22:25], v[134:135], off
	v_add_co_u32_e32 v138, vcc, s1, v124
	global_load_dwordx4 v[26:29], v[136:137], off
	s_nop 0
	v_addc_co_u32_e32 v139, vcc, 0, v125, vcc
	global_load_dwordx4 v[34:37], v[138:139], off
	global_load_dwordx4 v[38:41], v[122:123], off
	s_movk_i32 s1, 0x4000
	v_add_co_u32_e32 v154, vcc, s1, v122
	s_mov_b32 s1, 0xc000
	s_nop 0
	v_addc_co_u32_e32 v155, vcc, 0, v123, vcc
	v_add_co_u32_e32 v156, vcc, s72, v122
	global_load_dwordx4 v[42:45], v[154:155], off
	s_nop 0
	v_addc_co_u32_e32 v157, vcc, 0, v123, vcc
	v_add_co_u32_e32 v158, vcc, s1, v122
	global_load_dwordx4 v[46:49], v[156:157], off
	s_nop 0
	v_addc_co_u32_e32 v159, vcc, 0, v123, vcc
	global_load_dwordx4 v[50:53], v[158:159], off
	v_lshlrev_b32_e32 v33, 2, v32
	s_movk_i32 s1, 0x7c
	s_mov_b64 s[34:35], 0x4000
	v_lshl_add_u64 v[142:143], v[122:123], 0, s[34:35]
	s_mov_b64 s[34:35], 0x8000
	v_lshrrev_b32_e32 v31, 3, v32
	v_lshl_add_u64 v[150:151], v[122:123], 0, s[34:35]
	s_mov_b64 s[34:35], 0xc000
	v_readfirstlane_b32 s0, v32
	v_lshl_add_u64 v[152:153], v[122:123], 0, s[34:35]
	v_lshlrev_b32_e32 v54, 3, v32
	s_waitcnt vmcnt(11)
	v_cvt_pk_bf16_f32 v18, v18, v19
	v_cvt_pk_bf16_f32 v19, v20, v21
	v_and_b32_e32 v20, 0x60, v32
	v_bitop3_b32 v20, v33, v20, s1 bitop3:0x6c
	v_lshlrev_b32_e32 v20, 1, v20
	v_lshl_or_b32 v117, v30, 8, v20
	s_movk_i32 s1, 0x90
	v_mad_u64_u32 v[140:141], s[34:35], v31, s1, v[0:1]
	v_and_b32_e32 v0, 31, v32
	v_and_or_b32 v0, s0, 64, v0
	s_ashr_i32 s0, s0, 1
	s_andn2_b32 s0, s0, 63
	s_waitcnt vmcnt(10)
	v_cvt_pk_bf16_f32 v2, v2, v3
	v_cvt_pk_bf16_f32 v3, v4, v5
	ds_write2st64_b64 v117, v[18:19], v[2:3] offset1:4
	s_waitcnt vmcnt(9)
	v_cvt_pk_bf16_f32 v2, v6, v7
	v_cvt_pk_bf16_f32 v3, v8, v9
	s_waitcnt vmcnt(8)
	v_cvt_pk_bf16_f32 v4, v10, v11
	v_cvt_pk_bf16_f32 v5, v12, v13
	ds_write2st64_b64 v117, v[2:3], v[4:5] offset0:8 offset1:12
	s_waitcnt vmcnt(7)
	v_cvt_pk_bf16_f32 v2, v14, v15
	v_cvt_pk_bf16_f32 v3, v16, v17
	s_waitcnt vmcnt(6)
	v_cvt_pk_bf16_f32 v4, v22, v23
	v_cvt_pk_bf16_f32 v5, v24, v25
	ds_write2st64_b64 v117, v[2:3], v[4:5] offset0:16 offset1:20
	s_waitcnt vmcnt(5)
	v_cvt_pk_bf16_f32 v2, v26, v27
	v_cvt_pk_bf16_f32 v3, v28, v29
	s_waitcnt vmcnt(4)
	v_cvt_pk_bf16_f32 v4, v34, v35
	v_cvt_pk_bf16_f32 v5, v36, v37
	ds_write2st64_b64 v117, v[2:3], v[4:5] offset0:24 offset1:28
	v_lshrrev_b32_e32 v2, 1, v32
	v_and_b32_e32 v2, 16, v2
	v_mad_u32_u24 v0, v0, s1, v2
	v_and_b32_e32 v2, 16, v32
	v_and_or_b32 v2, v33, 12, v2
	v_and_b32_e32 v4, 0x60, v54
	v_or_b32_e32 v3, s0, v2
	v_bitop3_b32 v5, v2, v4, s0 bitop3:0x36
	s_mov_b32 s0, 0x40000
	v_add_co_u32_e32 v2, vcc, s0, v124
	v_bitop3_b32 v14, v3, v4, 32 bitop3:0x36
	s_nop 0
	v_addc_co_u32_e32 v3, vcc, 0, v125, vcc
	s_mov_b32 s0, 0x48000
	s_waitcnt vmcnt(3)
	ds_write_b128 v140, v[38:41] offset:32768
	s_waitcnt vmcnt(2)
	ds_write_b128 v140, v[42:45] offset:37376
	s_waitcnt vmcnt(1)
	ds_write_b128 v140, v[46:49] offset:41984
	s_waitcnt vmcnt(0)
	ds_write_b128 v140, v[50:53] offset:46592
	s_waitcnt lgkmcnt(0)
	s_barrier
	global_load_dwordx4 v[66:69], v[2:3], off
	v_add_co_u32_e32 v2, vcc, s0, v124
	s_mov_b32 s0, 0x50000
	s_nop 0
	v_addc_co_u32_e32 v3, vcc, 0, v125, vcc
	global_load_dwordx4 v[70:73], v[2:3], off
	v_add_co_u32_e32 v2, vcc, s0, v124
	s_mov_b32 s0, 0x58000
	s_nop 0
	v_addc_co_u32_e32 v3, vcc, 0, v125, vcc
	global_load_dwordx4 v[74:77], v[2:3], off
	v_add_co_u32_e32 v2, vcc, s0, v124
	s_mov_b32 s0, 0x60000
	s_nop 0
	v_addc_co_u32_e32 v3, vcc, 0, v125, vcc
	global_load_dwordx4 v[78:81], v[2:3], off
	v_add_co_u32_e32 v2, vcc, s0, v124
	s_mov_b32 s0, 0x68000
	s_nop 0
	v_addc_co_u32_e32 v3, vcc, 0, v125, vcc
	global_load_dwordx4 v[82:85], v[2:3], off
	v_add_co_u32_e32 v2, vcc, s0, v124
	s_mov_b32 s0, 0x70000
	s_nop 0
	v_addc_co_u32_e32 v3, vcc, 0, v125, vcc
	global_load_dwordx4 v[86:89], v[2:3], off
	v_add_co_u32_e32 v2, vcc, s0, v124
	s_mov_b32 s0, 0x78000
	s_nop 0
	v_addc_co_u32_e32 v3, vcc, 0, v125, vcc
	global_load_dwordx4 v[90:93], v[2:3], off
	v_add_co_u32_e32 v2, vcc, s0, v124
	s_nop 1
	v_addc_co_u32_e32 v3, vcc, 0, v125, vcc
	global_load_dwordx4 v[110:113], v[2:3], off
	global_load_dwordx4 v[94:97], v[122:123], off offset:128
	global_load_dwordx4 v[98:101], v[142:143], off offset:128
	global_load_dwordx4 v[102:105], v[150:151], off offset:128
	global_load_dwordx4 v[106:109], v[152:153], off offset:128
	v_lshlrev_b32_e32 v2, 6, v32
	v_and_b32_e32 v15, 0xb00, v2
	v_lshl_add_u32 v121, v5, 1, v15
	v_lshl_add_u32 v119, v14, 1, v15
	ds_read_b64_tr_b16 v[2:3], v121
	ds_read_b64_tr_b16 v[4:5], v121 offset:1024
	ds_read_b128 v[6:9], v0 offset:32768
	ds_read_b128 v[10:13], v0 offset:37376
	ds_read_b64_tr_b16 v[14:15], v119
	ds_read_b64_tr_b16 v[16:17], v119 offset:1024
	ds_read_b64_tr_b16 v[186:187], v121 offset:4096
	ds_read_b64_tr_b16 v[188:189], v121 offset:5120
	ds_read_b128 v[190:193], v0 offset:32800
	ds_read_b128 v[194:197], v0 offset:37408
	ds_read_b64_tr_b16 v[198:199], v119 offset:4096
	ds_read_b64_tr_b16 v[200:201], v119 offset:5120
	s_waitcnt lgkmcnt(9)
	v_mfma_f32_32x32x16_bf16 v[50:65], v[2:5], v[6:9], 0
	s_waitcnt lgkmcnt(8)
	v_mfma_f32_32x32x16_bf16 v[18:33], v[2:5], v[10:13], 0
	s_waitcnt lgkmcnt(6)
	v_mfma_f32_32x32x16_bf16 v[34:49], v[14:17], v[6:9], 0
	v_mfma_f32_32x32x16_bf16 v[2:17], v[14:17], v[10:13], 0
	s_waitcnt lgkmcnt(3)
	v_mfma_f32_32x32x16_bf16 v[50:65], v[186:189], v[190:193], v[50:65]
	s_waitcnt lgkmcnt(2)
	v_mfma_f32_32x32x16_bf16 v[18:33], v[186:189], v[194:197], v[18:33]
	s_waitcnt lgkmcnt(0)
	v_mfma_f32_32x32x16_bf16 v[34:49], v[198:201], v[190:193], v[34:49]
	ds_read_b64_tr_b16 v[186:187], v121 offset:8192
	ds_read_b64_tr_b16 v[188:189], v121 offset:9216
	ds_read_b128 v[190:193], v0 offset:32832
	v_mfma_f32_32x32x16_bf16 v[2:17], v[198:201], v[194:197], v[2:17]
	ds_read_b128 v[194:197], v0 offset:37440
	ds_read_b64_tr_b16 v[198:199], v119 offset:8192
	ds_read_b64_tr_b16 v[200:201], v119 offset:9216
	s_waitcnt lgkmcnt(3)
	v_mfma_f32_32x32x16_bf16 v[50:65], v[186:189], v[190:193], v[50:65]
	s_waitcnt lgkmcnt(2)
	v_mfma_f32_32x32x16_bf16 v[18:33], v[186:189], v[194:197], v[18:33]
	s_waitcnt lgkmcnt(0)
	v_mfma_f32_32x32x16_bf16 v[34:49], v[198:201], v[190:193], v[34:49]
	ds_read_b64_tr_b16 v[186:187], v121 offset:12288
	ds_read_b64_tr_b16 v[188:189], v121 offset:13312
	ds_read_b128 v[190:193], v0 offset:32864
	v_mfma_f32_32x32x16_bf16 v[2:17], v[198:201], v[194:197], v[2:17]
	ds_read_b128 v[194:197], v0 offset:37472
	ds_read_b64_tr_b16 v[198:199], v119 offset:12288
	ds_read_b64_tr_b16 v[200:201], v119 offset:13312
	s_waitcnt lgkmcnt(3)
	v_mfma_f32_32x32x16_bf16 v[50:65], v[186:189], v[190:193], v[50:65]
	s_waitcnt lgkmcnt(2)
	v_mfma_f32_32x32x16_bf16 v[18:33], v[186:189], v[194:197], v[18:33]
	s_waitcnt lgkmcnt(0)
	v_mfma_f32_32x32x16_bf16 v[34:49], v[198:201], v[190:193], v[34:49]
	v_mfma_f32_32x32x16_bf16 v[2:17], v[198:201], v[194:197], v[2:17]
	s_waitcnt vmcnt(11)
	v_cvt_pk_bf16_f32 v66, v66, v67
	v_cvt_pk_bf16_f32 v67, v68, v69
	s_waitcnt vmcnt(10)
	v_cvt_pk_bf16_f32 v68, v70, v71
	v_cvt_pk_bf16_f32 v69, v72, v73
	ds_write2st64_b64 v117, v[66:67], v[68:69] offset0:32 offset1:36
	s_waitcnt vmcnt(9)
	v_cvt_pk_bf16_f32 v66, v74, v75
	v_cvt_pk_bf16_f32 v67, v76, v77
	s_waitcnt vmcnt(8)
	v_cvt_pk_bf16_f32 v68, v78, v79
	v_cvt_pk_bf16_f32 v69, v80, v81
	ds_write2st64_b64 v117, v[66:67], v[68:69] offset0:40 offset1:44
	s_waitcnt vmcnt(7)
	v_cvt_pk_bf16_f32 v66, v82, v83
	v_cvt_pk_bf16_f32 v67, v84, v85
	s_waitcnt vmcnt(6)
	v_cvt_pk_bf16_f32 v68, v86, v87
	v_cvt_pk_bf16_f32 v69, v88, v89
	ds_write2st64_b64 v117, v[66:67], v[68:69] offset0:48 offset1:52
	s_waitcnt vmcnt(5)
	v_cvt_pk_bf16_f32 v66, v90, v91
	v_cvt_pk_bf16_f32 v67, v92, v93
	s_waitcnt vmcnt(4)
	v_cvt_pk_bf16_f32 v68, v110, v111
	v_cvt_pk_bf16_f32 v69, v112, v113
	s_mov_b32 s0, 0x80000
	ds_write2st64_b64 v117, v[66:67], v[68:69] offset0:56 offset1:60
	s_waitcnt vmcnt(3)
	ds_write_b128 v140, v[94:97] offset:51200
	s_waitcnt vmcnt(2)
	ds_write_b128 v140, v[98:101] offset:55808
	s_waitcnt vmcnt(1)
	ds_write_b128 v140, v[102:105] offset:60416
	s_waitcnt vmcnt(0)
	ds_write_b128 v140, v[106:109] offset:65024
	v_add_co_u32_e32 v66, vcc, s0, v124
	s_mov_b32 s0, 0x88000
	s_nop 0
	v_addc_co_u32_e32 v67, vcc, 0, v125, vcc
	v_add_co_u32_e32 v70, vcc, s0, v124
	s_mov_b32 s0, 0x90000
	s_nop 0
	v_addc_co_u32_e32 v71, vcc, 0, v125, vcc
	v_add_co_u32_e32 v74, vcc, s0, v124
	s_mov_b32 s0, 0x98000
	s_nop 0
	v_addc_co_u32_e32 v75, vcc, 0, v125, vcc
	v_add_co_u32_e32 v78, vcc, s0, v124
	s_mov_b32 s0, 0xa0000
	s_nop 0
	v_addc_co_u32_e32 v79, vcc, 0, v125, vcc
	v_add_co_u32_e32 v82, vcc, s0, v124
	s_mov_b32 s0, 0xa8000
	s_nop 0
	v_addc_co_u32_e32 v83, vcc, 0, v125, vcc
	v_add_co_u32_e32 v86, vcc, s0, v124
	s_mov_b32 s0, 0xb0000
	s_nop 0
	v_addc_co_u32_e32 v87, vcc, 0, v125, vcc
	v_add_co_u32_e32 v90, vcc, s0, v124
	s_mov_b32 s0, 0xb8000
	s_nop 0
	v_addc_co_u32_e32 v91, vcc, 0, v125, vcc
	v_add_co_u32_e32 v94, vcc, s0, v124
	s_waitcnt lgkmcnt(0)
	s_nop 0
	v_addc_co_u32_e32 v95, vcc, 0, v125, vcc
	s_barrier
	global_load_dwordx4 v[66:69], v[66:67], off
	s_nop 0
	global_load_dwordx4 v[70:73], v[70:71], off
	s_nop 0
	global_load_dwordx4 v[74:77], v[74:75], off
	s_nop 0
	global_load_dwordx4 v[78:81], v[78:79], off
	s_nop 0
	global_load_dwordx4 v[82:85], v[82:83], off
	s_nop 0
	global_load_dwordx4 v[86:89], v[86:87], off
	s_nop 0
	global_load_dwordx4 v[90:93], v[90:91], off
	s_nop 0
	global_load_dwordx4 v[94:97], v[94:95], off
	s_nop 0
	global_load_dwordx4 v[98:101], v[122:123], off offset:256
	global_load_dwordx4 v[102:105], v[142:143], off offset:256
	global_load_dwordx4 v[106:109], v[150:151], off offset:256
	global_load_dwordx4 v[110:113], v[152:153], off offset:256
	ds_read_b64_tr_b16 v[186:187], v121 offset:16384
	ds_read_b64_tr_b16 v[188:189], v121 offset:17408
	ds_read_b128 v[190:193], v0 offset:51200
	ds_read_b128 v[194:197], v0 offset:55808
	ds_read_b64_tr_b16 v[198:199], v119 offset:16384
	ds_read_b64_tr_b16 v[200:201], v119 offset:17408
	s_waitcnt lgkmcnt(2)
	v_mfma_f32_32x32x16_bf16 v[18:33], v[186:189], v[194:197], v[18:33]
	v_mfma_f32_32x32x16_bf16 v[50:65], v[186:189], v[190:193], v[50:65]
	s_waitcnt lgkmcnt(0)
	v_mfma_f32_32x32x16_bf16 v[34:49], v[198:201], v[190:193], v[34:49]
	ds_read_b64_tr_b16 v[186:187], v121 offset:20480
	ds_read_b64_tr_b16 v[188:189], v121 offset:21504
	ds_read_b128 v[190:193], v0 offset:51232
	v_mfma_f32_32x32x16_bf16 v[2:17], v[198:201], v[194:197], v[2:17]
	ds_read_b128 v[194:197], v0 offset:55840
	ds_read_b64_tr_b16 v[198:199], v119 offset:20480
	ds_read_b64_tr_b16 v[200:201], v119 offset:21504
	s_waitcnt lgkmcnt(3)
	v_mfma_f32_32x32x16_bf16 v[50:65], v[186:189], v[190:193], v[50:65]
	s_waitcnt lgkmcnt(2)
	v_mfma_f32_32x32x16_bf16 v[18:33], v[186:189], v[194:197], v[18:33]
	s_waitcnt lgkmcnt(0)
	v_mfma_f32_32x32x16_bf16 v[34:49], v[198:201], v[190:193], v[34:49]
	ds_read_b64_tr_b16 v[186:187], v121 offset:24576
	ds_read_b64_tr_b16 v[188:189], v121 offset:25600
	ds_read_b128 v[190:193], v0 offset:51264
	v_mfma_f32_32x32x16_bf16 v[2:17], v[198:201], v[194:197], v[2:17]
	ds_read_b128 v[194:197], v0 offset:55872
	ds_read_b64_tr_b16 v[198:199], v119 offset:24576
	ds_read_b64_tr_b16 v[200:201], v119 offset:25600
	s_waitcnt lgkmcnt(3)
	v_mfma_f32_32x32x16_bf16 v[50:65], v[186:189], v[190:193], v[50:65]
	s_waitcnt lgkmcnt(2)
	v_mfma_f32_32x32x16_bf16 v[18:33], v[186:189], v[194:197], v[18:33]
	s_waitcnt lgkmcnt(0)
	v_mfma_f32_32x32x16_bf16 v[34:49], v[198:201], v[190:193], v[34:49]
	ds_read_b64_tr_b16 v[186:187], v121 offset:28672
	ds_read_b64_tr_b16 v[188:189], v121 offset:29696
	ds_read_b128 v[190:193], v0 offset:51296
	v_mfma_f32_32x32x16_bf16 v[2:17], v[198:201], v[194:197], v[2:17]
	ds_read_b128 v[194:197], v0 offset:55904
	ds_read_b64_tr_b16 v[198:199], v119 offset:28672
	ds_read_b64_tr_b16 v[200:201], v119 offset:29696
	s_waitcnt lgkmcnt(3)
	v_mfma_f32_32x32x16_bf16 v[50:65], v[186:189], v[190:193], v[50:65]
	s_waitcnt lgkmcnt(2)
	v_mfma_f32_32x32x16_bf16 v[18:33], v[186:189], v[194:197], v[18:33]
	s_waitcnt lgkmcnt(0)
	v_mfma_f32_32x32x16_bf16 v[34:49], v[198:201], v[190:193], v[34:49]
	v_mfma_f32_32x32x16_bf16 v[2:17], v[198:201], v[194:197], v[2:17]
	s_waitcnt vmcnt(11)
	v_cvt_pk_bf16_f32 v66, v66, v67
	v_cvt_pk_bf16_f32 v67, v68, v69
	s_waitcnt vmcnt(10)
	v_cvt_pk_bf16_f32 v68, v70, v71
	v_cvt_pk_bf16_f32 v69, v72, v73
	ds_write2st64_b64 v117, v[66:67], v[68:69] offset1:4
	s_waitcnt vmcnt(9)
	v_cvt_pk_bf16_f32 v66, v74, v75
	v_cvt_pk_bf16_f32 v67, v76, v77
	s_waitcnt vmcnt(8)
	v_cvt_pk_bf16_f32 v68, v78, v79
	v_cvt_pk_bf16_f32 v69, v80, v81
	ds_write2st64_b64 v117, v[66:67], v[68:69] offset0:8 offset1:12
	s_waitcnt vmcnt(7)
	v_cvt_pk_bf16_f32 v66, v82, v83
	v_cvt_pk_bf16_f32 v67, v84, v85
	s_waitcnt vmcnt(6)
	v_cvt_pk_bf16_f32 v68, v86, v87
	v_cvt_pk_bf16_f32 v69, v88, v89
	ds_write2st64_b64 v117, v[66:67], v[68:69] offset0:16 offset1:20
	s_waitcnt vmcnt(5)
	v_cvt_pk_bf16_f32 v66, v90, v91
	v_cvt_pk_bf16_f32 v67, v92, v93
	s_waitcnt vmcnt(4)
	v_cvt_pk_bf16_f32 v68, v94, v95
	v_cvt_pk_bf16_f32 v69, v96, v97
	s_mov_b32 s0, 0xc0000
	ds_write2st64_b64 v117, v[66:67], v[68:69] offset0:24 offset1:28
	s_waitcnt vmcnt(3)
	ds_write_b128 v140, v[98:101] offset:32768
	s_waitcnt vmcnt(2)
	ds_write_b128 v140, v[102:105] offset:37376
	s_waitcnt vmcnt(1)
	ds_write_b128 v140, v[106:109] offset:41984
	s_waitcnt vmcnt(0)
	ds_write_b128 v140, v[110:113] offset:46592
	v_add_co_u32_e32 v66, vcc, s0, v124
	s_mov_b32 s0, 0xc8000
	s_nop 0
	v_addc_co_u32_e32 v67, vcc, 0, v125, vcc
	v_add_co_u32_e32 v70, vcc, s0, v124
	s_mov_b32 s0, 0xd0000
	s_nop 0
	v_addc_co_u32_e32 v71, vcc, 0, v125, vcc
	v_add_co_u32_e32 v74, vcc, s0, v124
	s_mov_b32 s0, 0xd8000
	s_nop 0
	v_addc_co_u32_e32 v75, vcc, 0, v125, vcc
	v_add_co_u32_e32 v78, vcc, s0, v124
	s_mov_b32 s0, 0xe0000
	s_nop 0
	v_addc_co_u32_e32 v79, vcc, 0, v125, vcc
	v_add_co_u32_e32 v82, vcc, s0, v124
	s_mov_b32 s0, 0xe8000
	s_nop 0
	v_addc_co_u32_e32 v83, vcc, 0, v125, vcc
	v_add_co_u32_e32 v86, vcc, s0, v124
	s_mov_b32 s0, 0xf0000
	s_nop 0
	v_addc_co_u32_e32 v87, vcc, 0, v125, vcc
	v_add_co_u32_e32 v90, vcc, s0, v124
	s_mov_b32 s0, 0xf8000
	s_nop 0
	v_addc_co_u32_e32 v91, vcc, 0, v125, vcc
	v_add_co_u32_e32 v94, vcc, s0, v124
	s_waitcnt lgkmcnt(0)
	s_nop 0
	v_addc_co_u32_e32 v95, vcc, 0, v125, vcc
	s_barrier
	global_load_dwordx4 v[66:69], v[66:67], off
	s_nop 0
	global_load_dwordx4 v[70:73], v[70:71], off
	s_nop 0
	global_load_dwordx4 v[74:77], v[74:75], off
	s_nop 0
	global_load_dwordx4 v[78:81], v[78:79], off
	s_nop 0
	global_load_dwordx4 v[82:85], v[82:83], off
	s_nop 0
	global_load_dwordx4 v[86:89], v[86:87], off
	s_nop 0
	global_load_dwordx4 v[90:93], v[90:91], off
	s_nop 0
	global_load_dwordx4 v[94:97], v[94:95], off
	s_nop 0
	global_load_dwordx4 v[98:101], v[122:123], off offset:384
	global_load_dwordx4 v[102:105], v[142:143], off offset:384
	global_load_dwordx4 v[106:109], v[150:151], off offset:384
	global_load_dwordx4 v[110:113], v[152:153], off offset:384
	ds_read_b64_tr_b16 v[150:151], v121
	ds_read_b64_tr_b16 v[152:153], v121 offset:1024
	ds_read_b128 v[186:189], v0 offset:32768
	ds_read_b128 v[190:193], v0 offset:37376
	ds_read_b64_tr_b16 v[194:195], v119
	ds_read_b64_tr_b16 v[196:197], v119 offset:1024
	s_waitcnt lgkmcnt(2)
	v_mfma_f32_32x32x16_bf16 v[18:33], v[150:153], v[190:193], v[18:33]
	v_mfma_f32_32x32x16_bf16 v[50:65], v[150:153], v[186:189], v[50:65]
	s_waitcnt lgkmcnt(0)
	v_mfma_f32_32x32x16_bf16 v[34:49], v[194:197], v[186:189], v[34:49]
	ds_read_b64_tr_b16 v[150:151], v121 offset:4096
	ds_read_b64_tr_b16 v[152:153], v121 offset:5120
	ds_read_b128 v[186:189], v0 offset:32800
	v_mfma_f32_32x32x16_bf16 v[2:17], v[194:197], v[190:193], v[2:17]
	ds_read_b128 v[190:193], v0 offset:37408
	ds_read_b64_tr_b16 v[194:195], v119 offset:4096
	ds_read_b64_tr_b16 v[196:197], v119 offset:5120
	s_waitcnt lgkmcnt(3)
	v_mfma_f32_32x32x16_bf16 v[50:65], v[150:153], v[186:189], v[50:65]
	s_waitcnt lgkmcnt(2)
	v_mfma_f32_32x32x16_bf16 v[18:33], v[150:153], v[190:193], v[18:33]
	s_waitcnt lgkmcnt(0)
	v_mfma_f32_32x32x16_bf16 v[34:49], v[194:197], v[186:189], v[34:49]
	ds_read_b64_tr_b16 v[150:151], v121 offset:8192
	ds_read_b64_tr_b16 v[152:153], v121 offset:9216
	ds_read_b128 v[186:189], v0 offset:32832
	v_mfma_f32_32x32x16_bf16 v[2:17], v[194:197], v[190:193], v[2:17]
	ds_read_b128 v[190:193], v0 offset:37440
	ds_read_b64_tr_b16 v[194:195], v119 offset:8192
	ds_read_b64_tr_b16 v[196:197], v119 offset:9216
	s_waitcnt lgkmcnt(3)
	v_mfma_f32_32x32x16_bf16 v[50:65], v[150:153], v[186:189], v[50:65]
	s_waitcnt lgkmcnt(2)
	v_mfma_f32_32x32x16_bf16 v[18:33], v[150:153], v[190:193], v[18:33]
	s_waitcnt lgkmcnt(0)
	v_mfma_f32_32x32x16_bf16 v[34:49], v[194:197], v[186:189], v[34:49]
	ds_read_b64_tr_b16 v[150:151], v121 offset:12288
	ds_read_b64_tr_b16 v[152:153], v121 offset:13312
	ds_read_b128 v[186:189], v0 offset:32864
	v_mfma_f32_32x32x16_bf16 v[2:17], v[194:197], v[190:193], v[2:17]
	ds_read_b128 v[190:193], v0 offset:37472
	ds_read_b64_tr_b16 v[194:195], v119 offset:12288
	ds_read_b64_tr_b16 v[196:197], v119 offset:13312
	s_waitcnt lgkmcnt(3)
	v_mfma_f32_32x32x16_bf16 v[50:65], v[150:153], v[186:189], v[50:65]
	s_waitcnt lgkmcnt(2)
	v_mfma_f32_32x32x16_bf16 v[18:33], v[150:153], v[190:193], v[18:33]
	s_waitcnt lgkmcnt(0)
	v_mfma_f32_32x32x16_bf16 v[34:49], v[194:197], v[186:189], v[34:49]
	v_mfma_f32_32x32x16_bf16 v[2:17], v[194:197], v[190:193], v[2:17]
	s_waitcnt vmcnt(11)
	v_cvt_pk_bf16_f32 v66, v66, v67
	v_cvt_pk_bf16_f32 v67, v68, v69
	s_waitcnt vmcnt(10)
	v_cvt_pk_bf16_f32 v68, v70, v71
	v_cvt_pk_bf16_f32 v69, v72, v73
	ds_write2st64_b64 v117, v[66:67], v[68:69] offset0:32 offset1:36
	s_waitcnt vmcnt(9)
	v_cvt_pk_bf16_f32 v66, v74, v75
	v_cvt_pk_bf16_f32 v67, v76, v77
	s_waitcnt vmcnt(8)
	v_cvt_pk_bf16_f32 v68, v78, v79
	v_cvt_pk_bf16_f32 v69, v80, v81
	ds_write2st64_b64 v117, v[66:67], v[68:69] offset0:40 offset1:44
	s_waitcnt vmcnt(7)
	v_cvt_pk_bf16_f32 v66, v82, v83
	v_cvt_pk_bf16_f32 v67, v84, v85
	s_waitcnt vmcnt(6)
	v_cvt_pk_bf16_f32 v68, v86, v87
	v_cvt_pk_bf16_f32 v69, v88, v89
	ds_write2st64_b64 v117, v[66:67], v[68:69] offset0:48 offset1:52
	s_waitcnt vmcnt(5)
	v_cvt_pk_bf16_f32 v66, v90, v91
	v_cvt_pk_bf16_f32 v67, v92, v93
	s_waitcnt vmcnt(4)
	v_cvt_pk_bf16_f32 v68, v94, v95
	v_cvt_pk_bf16_f32 v69, v96, v97
	ds_write2st64_b64 v117, v[66:67], v[68:69] offset0:56 offset1:60
	s_waitcnt vmcnt(3)
	ds_write_b128 v140, v[98:101] offset:51200
	s_waitcnt vmcnt(2)
	ds_write_b128 v140, v[102:105] offset:55808
	s_waitcnt vmcnt(1)
	ds_write_b128 v140, v[106:109] offset:60416
	s_waitcnt vmcnt(0)
	ds_write_b128 v140, v[110:113] offset:65024
	s_waitcnt lgkmcnt(0)
	s_barrier
	ds_read_b64_tr_b16 v[122:123], v121 offset:16384
	ds_read_b64_tr_b16 v[124:125], v121 offset:17408
	ds_read_b128 v[126:129], v0 offset:51200
	ds_read_b128 v[130:133], v0 offset:55808
	ds_read_b64_tr_b16 v[134:135], v119 offset:16384
	ds_read_b64_tr_b16 v[136:137], v119 offset:17408
	s_waitcnt lgkmcnt(2)
	v_mfma_f32_32x32x16_bf16 v[18:33], v[122:125], v[130:133], v[18:33]
	v_mfma_f32_32x32x16_bf16 v[50:65], v[122:125], v[126:129], v[50:65]
	s_waitcnt lgkmcnt(0)
	v_mfma_f32_32x32x16_bf16 v[34:49], v[134:137], v[126:129], v[34:49]
	ds_read_b64_tr_b16 v[122:123], v121 offset:20480
	ds_read_b64_tr_b16 v[124:125], v121 offset:21504
	ds_read_b128 v[126:129], v0 offset:51232
	v_mfma_f32_32x32x16_bf16 v[2:17], v[134:137], v[130:133], v[2:17]
	ds_read_b128 v[130:133], v0 offset:55840
	ds_read_b64_tr_b16 v[134:135], v119 offset:20480
	ds_read_b64_tr_b16 v[136:137], v119 offset:21504
	s_waitcnt lgkmcnt(3)
	v_mfma_f32_32x32x16_bf16 v[50:65], v[122:125], v[126:129], v[50:65]
	s_waitcnt lgkmcnt(2)
	v_mfma_f32_32x32x16_bf16 v[18:33], v[122:125], v[130:133], v[18:33]
	s_waitcnt lgkmcnt(0)
	v_mfma_f32_32x32x16_bf16 v[34:49], v[134:137], v[126:129], v[34:49]
	ds_read_b64_tr_b16 v[122:123], v121 offset:24576
	ds_read_b64_tr_b16 v[124:125], v121 offset:25600
	ds_read_b128 v[126:129], v0 offset:51264
	v_mfma_f32_32x32x16_bf16 v[2:17], v[134:137], v[130:133], v[2:17]
	ds_read_b128 v[130:133], v0 offset:55872
	ds_read_b64_tr_b16 v[134:135], v119 offset:24576
	ds_read_b64_tr_b16 v[136:137], v119 offset:25600
	s_waitcnt lgkmcnt(3)
	v_mfma_f32_32x32x16_bf16 v[50:65], v[122:125], v[126:129], v[50:65]
	s_waitcnt lgkmcnt(2)
	v_mfma_f32_32x32x16_bf16 v[18:33], v[122:125], v[130:133], v[18:33]
	s_waitcnt lgkmcnt(0)
	v_mfma_f32_32x32x16_bf16 v[34:49], v[134:137], v[126:129], v[34:49]
	ds_read_b64_tr_b16 v[122:123], v121 offset:28672
	ds_read_b64_tr_b16 v[124:125], v121 offset:29696
	ds_read_b128 v[126:129], v0 offset:51296
	v_mfma_f32_32x32x16_bf16 v[2:17], v[134:137], v[130:133], v[2:17]
	ds_read_b128 v[130:133], v0 offset:55904
	ds_read_b64_tr_b16 v[134:135], v119 offset:28672
	ds_read_b64_tr_b16 v[136:137], v119 offset:29696
	s_waitcnt lgkmcnt(3)
	v_mfma_f32_32x32x16_bf16 v[50:65], v[122:125], v[126:129], v[50:65]
	s_waitcnt lgkmcnt(2)
	v_mfma_f32_32x32x16_bf16 v[18:33], v[122:125], v[130:133], v[18:33]
	s_waitcnt lgkmcnt(0)
	v_mfma_f32_32x32x16_bf16 v[34:49], v[134:137], v[126:129], v[34:49]
	v_mfma_f32_32x32x16_bf16 v[2:17], v[134:137], v[130:133], v[2:17]
	s_lshl_b32 s0, s14, 1
	s_add_u32 s14, s22, s0
	s_addc_u32 s15, s23, 0
	s_ashr_i32 s0, s13, 1
	s_andn2_b32 s0, s0, 63
	s_ashr_i32 s1, s0, 31
	s_lshl_b64 s[0:1], s[0:1], 1
	s_add_u32 s0, s14, s0
	v_lshrrev_b32_e32 v0, 2, v115
	s_addc_u32 s1, s15, s1
	v_and_b32_e32 v0, 8, v0
	v_lshl_add_u64 v[66:67], s[0:1], 0, v[0:1]
	v_cmp_lt_i32_e32 vcc, -1, v120
	s_waitcnt lgkmcnt(0)
	s_barrier
	s_and_saveexec_b64 s[0:1], vcc
	s_cbranch_execz .LBB0_902
	v_mov_b32_e32 v121, v1
	v_lshlrev_b64 v[68:69], 11, v[120:121]
	v_pk_mul_f32 v[50:51], v[116:117], v[50:51] op_sel_hi:[0,1]
	v_pk_mul_f32 v[52:53], v[116:117], v[52:53] op_sel_hi:[0,1]
	v_pk_mul_f32 v[34:35], v[116:117], v[34:35] op_sel_hi:[0,1]
	v_pk_mul_f32 v[36:37], v[116:117], v[36:37] op_sel_hi:[0,1]
	v_lshl_add_u64 v[68:69], v[66:67], 0, v[68:69]
	v_cvt_pk_bf16_f32 v50, v50, v51
	v_cvt_pk_bf16_f32 v51, v52, v53
	v_cvt_pk_bf16_f32 v34, v34, v35
	v_cvt_pk_bf16_f32 v35, v36, v37
	global_store_dwordx2 v[68:69], v[50:51], off
	v_pk_mul_f32 v[50:51], v[116:117], v[54:55] op_sel_hi:[0,1]
	v_pk_mul_f32 v[52:53], v[116:117], v[56:57] op_sel_hi:[0,1]
	global_store_dwordx2 v[68:69], v[34:35], off offset:64
	v_pk_mul_f32 v[34:35], v[116:117], v[38:39] op_sel_hi:[0,1]
	v_pk_mul_f32 v[36:37], v[116:117], v[40:41] op_sel_hi:[0,1]
	v_cvt_pk_bf16_f32 v50, v50, v51
	v_cvt_pk_bf16_f32 v51, v52, v53
	v_cvt_pk_bf16_f32 v34, v34, v35
	v_cvt_pk_bf16_f32 v35, v36, v37
	global_store_dwordx2 v[68:69], v[50:51], off offset:16
	v_pk_mul_f32 v[50:51], v[116:117], v[58:59] op_sel_hi:[0,1]
	v_pk_mul_f32 v[52:53], v[116:117], v[60:61] op_sel_hi:[0,1]
	global_store_dwordx2 v[68:69], v[34:35], off offset:80
	v_pk_mul_f32 v[34:35], v[116:117], v[42:43] op_sel_hi:[0,1]
	v_pk_mul_f32 v[36:37], v[116:117], v[44:45] op_sel_hi:[0,1]
	v_cvt_pk_bf16_f32 v50, v50, v51
	v_cvt_pk_bf16_f32 v51, v52, v53
	v_cvt_pk_bf16_f32 v34, v34, v35
	v_cvt_pk_bf16_f32 v35, v36, v37
	global_store_dwordx2 v[68:69], v[50:51], off offset:32
	v_pk_mul_f32 v[50:51], v[116:117], v[62:63] op_sel_hi:[0,1]
	v_pk_mul_f32 v[52:53], v[116:117], v[64:65] op_sel_hi:[0,1]
	global_store_dwordx2 v[68:69], v[34:35], off offset:96
	v_pk_mul_f32 v[34:35], v[116:117], v[46:47] op_sel_hi:[0,1]
	v_pk_mul_f32 v[36:37], v[116:117], v[48:49] op_sel_hi:[0,1]
	v_cvt_pk_bf16_f32 v50, v50, v51
	v_cvt_pk_bf16_f32 v51, v52, v53
	v_cvt_pk_bf16_f32 v34, v34, v35
	v_cvt_pk_bf16_f32 v35, v36, v37
	global_store_dwordx2 v[68:69], v[50:51], off offset:48
	global_store_dwordx2 v[68:69], v[34:35], off offset:112
